# mixer loop: counted waits at the item boundary leave the eight epilogue stores in flight (only the prefetched loads are waited for)
# speedup vs baseline: 1.0098x; 1.0040x over previous
.LBB0_653:
	v_and_b32_e32 v28, 15, v30
	v_lshrrev_b32_e32 v29, 2, v30
	s_mov_b32 s4, 0x1fffff0
	v_and_or_b32 v28, v29, s4, v28
	v_lshlrev_b32_e32 v28, 7, v28
	v_ashrrev_i32_e32 v29, 31, v28
	v_lshl_add_u64 v[32:33], v[28:29], 1, s[0:1]
	v_lshrrev_b32_e32 v28, 1, v30
	v_and_b32_e32 v28, 24, v28
	v_mov_b32_e32 v29, 0
	v_lshl_add_u64 v[30:31], v[32:33], 0, v[28:29]
	global_load_dwordx2 v[170:171], v[30:31], off
	global_load_dwordx2 v[168:169], v[30:31], off offset:32
	global_load_dwordx2 v[166:167], v[30:31], off offset:64
	global_load_dwordx2 v[162:163], v[30:31], off offset:96
	global_load_dwordx2 v[156:157], v[30:31], off offset:224
	global_load_dwordx2 v[160:161], v[30:31], off offset:192
	global_load_dwordx2 v[164:165], v[30:31], off offset:160
	global_load_dwordx2 v[158:159], v[30:31], off offset:128
	s_add_u32 s4, s76, 0x447c000
	s_addc_u32 s5, s77, 0
	s_add_u32 s6, s76, 0x4080000
	s_addc_u32 s7, s77, 0
	s_mov_b32 s9, 0
	s_movk_i32 s15, 0x110
	s_mov_b32 s14, 0x3b000000
	s_mov_b32 s23, 0x800000
	s_mov_b32 s24, 0x7ffffff8
	s_add_i32 s25, 0, 0x11000
	s_movk_i32 s33, 0x900
	s_movk_i32 s80, 0x440
	s_add_i32 s81, 0, 0x12100
	s_add_i32 s82, 0, 0x12210
	v_mov_b32_e32 v173, 0x3800
	s_mov_b32 s83, s13
	s_waitcnt vmcnt(0)
	s_branch .LBB0_656

.LBB0_655:
	v_lshl_add_u64 v[104:105], v[28:29], 1, v[156:157]
	global_store_dwordx2 v[104:105], v[160:161], off offset:224
	s_add_i32 s83, s83, s12
	s_andn2_b64 vcc, exec, s[36:37]
	s_waitcnt vmcnt(11)
	v_mov_b64_e32 v[158:159], v[186:187]
	v_mov_b64_e32 v[162:163], v[184:185]
	v_mov_b64_e32 v[166:167], v[182:183]
	v_mov_b64_e32 v[168:169], v[180:181]
	v_mov_b64_e32 v[170:171], v[178:179]
	s_waitcnt vmcnt(10)
	v_mov_b64_e32 v[164:165], v[176:177]
	s_waitcnt vmcnt(9)
	v_mov_b64_e32 v[160:161], v[174:175]
	s_waitcnt vmcnt(8)
	v_mov_b64_e32 v[156:157], v[30:31]
	s_cbranch_vccz .LBB0_746
.LBB0_656:
	s_ashr_i32 s0, s13, 3
	s_add_i32 s84, s0, -1
	s_add_i32 s0, s0, s13
	s_and_b32 s38, s0, 3
	v_mov_b32_e32 v129, v202
	s_bitcmp1_b32 s0, 2
	s_cselect_b64 s[16:17], -1, 0
	v_lshlrev_b32_e32 v28, 4, v129
	v_add_u32_e32 v132, 0x200, v129
	v_add_u32_e32 v131, 0x400, v129
	v_add_u32_e32 v130, 0x600, v129
	v_and_b32_e32 v128, 15, v129
	v_ashrrev_i32_e32 v133, 4, v129
	s_ashr_i32 s39, s84, 4
	s_and_b32 s64, s84, 15
	s_mov_b64 s[0:1], -1
	s_and_b64 vcc, exec, s[16:17]
	v_and_b32_e32 v134, 0xf0, v28
	v_lshrrev_b32_e32 v137, 4, v132
	v_lshrrev_b32_e32 v136, 4, v131
	v_lshrrev_b32_e32 v135, 4, v130
	s_waitcnt vmcnt(8) lgkmcnt(0)
	s_barrier
	s_cbranch_vccz .LBB0_666
	s_lshl_b32 s8, s38, 7
	v_lshlrev_b32_e32 v138, 3, v128
	v_or_b32_e32 v28, s8, v138
	v_lshlrev_b32_e32 v28, 2, v28
	global_load_dwordx4 v[104:107], v28, s[60:61] offset:16
	global_load_dwordx4 v[112:115], v28, s[60:61]
	global_load_dwordx4 v[108:111], v28, s[62:63] offset:16
	global_load_dwordx4 v[116:119], v28, s[62:63]
	v_add_u32_e32 v30, 0, v134
	v_mad_u64_u32 v[120:121], s[0:1], v133, s15, v[30:31]
	ds_write_b128 v120, v[12:15] offset:34816
	v_mad_u64_u32 v[120:121], s[0:1], v137, s15, v[30:31]
	ds_write_b128 v120, v[20:23] offset:34816
	v_mad_u64_u32 v[120:121], s[0:1], v136, s15, v[30:31]
	v_mad_u64_u32 v[30:31], s[0:1], v135, s15, v[30:31]
	v_lshrrev_b32_e32 v31, 3, v129
	ds_write_b128 v120, v[24:27] offset:34816
	ds_write_b128 v30, v[96:99] offset:34816
	v_mul_u32_u24_e32 v30, 0x880, v128
	v_and_b32_e32 v31, 14, v31
	v_pk_mul_f32 v[124:125], v[148:149], s[14:15] op_sel_hi:[1,0]
	v_add3_u32 v139, 0, v30, v31
	v_lshl_add_u64 v[30:31], s[4:5], 0, v[28:29]
	v_fma_f32 v28, -v124, v124, v125
	v_max_f32_e32 v28, 0, v28
	v_add_f32_e32 v28, 0x358637bd, v28
	v_cmp_gt_f32_e32 vcc, s23, v28
	v_mul_f32_e32 v120, 0x4b800000, v28
	v_lshlrev_b32_e32 v122, 16, v0
	v_cndmask_b32_e32 v28, v28, v120, vcc
	v_rsq_f32_e32 v28, v28
	v_and_b32_e32 v123, 0xffff0000, v0
	v_and_b32_e32 v121, 0xffff0000, v1
	v_sub_f32_e32 v121, v121, v124
	v_mul_f32_e32 v120, 0x45800000, v28
	v_cndmask_b32_e32 v28, v28, v120, vcc
	v_lshlrev_b32_e32 v120, 16, v1
	v_sub_f32_e32 v120, v120, v124
	v_sub_f32_e32 v123, v123, v124
	v_sub_f32_e32 v122, v122, v124
	v_lshlrev_b32_e32 v140, 16, v2
	v_and_b32_e32 v125, 0xffff0000, v2
	v_lshlrev_b32_e32 v141, 16, v3
	v_and_b32_e32 v142, 0xffff0000, v3
	v_pk_mul_f32 v[126:127], v[122:123], v[28:29] op_sel_hi:[1,0]
	v_pk_mul_f32 v[120:121], v[120:121], v[28:29] op_sel_hi:[1,0]
	s_cmp_eq_u32 s64, 15
	v_sub_f32_e32 v125, v125, v124
	s_cselect_b64 s[36:37], -1, 0
	s_lshl_b32 s65, s39, 7
	v_bitop3_b32 v143, v133, v138, s24 bitop3:0x6c
	s_cmp_lg_u32 s64, 15
	v_lshl_add_u32 v143, v143, 1, v139
	s_waitcnt vmcnt(0)
	v_pk_fma_f32 v[122:123], v[120:121], v[114:115], v[118:119]
	v_pk_fma_f32 v[120:121], v[126:127], v[112:113], v[116:117]
	v_sub_f32_e32 v127, v142, v124
	v_sub_f32_e32 v126, v141, v124
	v_sub_f32_e32 v124, v140, v124
	v_pk_mul_f32 v[124:125], v[124:125], v[28:29] op_sel_hi:[1,0]
	v_pk_mul_f32 v[126:127], v[126:127], v[28:29] op_sel_hi:[1,0]
	v_pk_fma_f32 v[124:125], v[124:125], v[104:105], v[108:109]
	v_pk_fma_f32 v[126:127], v[126:127], v[106:107], v[110:111]
	v_cvt_pk_bf16_f32 v28, v120, v121
	v_cvt_pk_bf16_f32 v140, v122, v123
	v_cvt_pk_bf16_f32 v141, v124, v125
	s_nop 0
	v_cvt_pk_bf16_f32 v142, v126, v127
	ds_write_b16 v143, v28
	ds_write_b16_d16_hi v143, v28 offset:272
	ds_write_b16 v143, v140 offset:544
	ds_write_b16_d16_hi v143, v140 offset:816
	ds_write_b16 v143, v141 offset:1088
	ds_write_b16_d16_hi v143, v141 offset:1360
	ds_write_b16 v143, v142 offset:1632
	ds_write_b16_d16_hi v143, v142 offset:1904
	s_cbranch_scc1 .LBB0_659
	v_add_u32_e32 v140, s65, v133
	v_ashrrev_i32_e32 v141, 31, v140
	v_lshlrev_b64 v[140:141], 11, v[140:141]
	v_lshl_add_u64 v[140:141], v[30:31], 0, v[140:141]
	global_store_dwordx4 v[140:141], v[120:123], off
	global_store_dwordx4 v[140:141], v[124:127], off offset:16
